# attention loop: VALU work issued ahead of the first MFMA of each compute segment to cover the LDS fragment latency (QK segments: 12 ops hoisted; PV segments: first gap filled)
# speedup vs baseline: 1.0029x; 1.0029x over previous
; __device__ __forceinline__ void finishSM(f32x16& p0, f32x16& p1, float alpha, float& l_reg, bf16x8& pa0, bf16x8& pa1, bf16x8& pa2, bf16x8& pa3) {
; #pragma unroll
;     for (int r = 0; r < 16; ++r) p1[r] = __builtin_amdgcn_exp2f(p1[r]);
;     float ps = 0;
; #pragma unroll
;     for (int r = 0; r < 16; ++r) ps += p0[r];
; #pragma unroll
;     for (int r = 0; r < 16; ++r) ps += p1[r];
;     { auto rr = __builtin_amdgcn_permlane32_swap(__float_as_uint(ps), __float_as_uint(ps), false, false);
;       ps = __uint_as_float(rr[0]) + __uint_as_float(rr[1]); }
;     l_reg = l_reg * alpha + ps;
;     ...
;     PK4(p0, 0, pa0); PK4(p0, 8, pa1); PK4(p1, 0, pa2); PK4(p1, 8, pa3);
;     ...
; }
; template <int KB>
; __device__ __forceinline__ void qkt(f32x16& p0, f32x16& p1, const char* K_lds, int r32, int hi, const bf16x8* qr) {
;     p0 = f32x16{}; p1 = f32x16{};
;     const char* kb[4];
; #pragma unroll
;     for (int dd = 0; dd < 4; ++dd) kb[dd] = K_lds + KB * SHM_K + KSWZ(r32, (dd * 16 + hi * 8) * 2);
; #pragma unroll
;     for (int d0 = 0; d0 < 8; ++d0) { const char* a = kb[d0 & 3] + (d0 >> 2) * 128;
;         bf16x8 b0 = *reinterpret_cast<const bf16x8*>(a);
;         bf16x8 b1 = *reinterpret_cast<const bf16x8*>(a + 32 * 256);
;         p0 = __builtin_amdgcn_mfma_f32_32x32x16_bf16(b0, qr[d0], p0, 0, 0, 0);
;         p1 = __builtin_amdgcn_mfma_f32_32x32x16_bf16(b1, qr[d0], p1, 0, 0, 0); }
; }
; template <int VB>
; __device__ __forceinline__ void pv_tile(f32x16* o, int vb0, bf16x8 pa0, bf16x8 pa1, bf16x8 pa2, bf16x8 pa3) {
;     ...
;     PV_D0(0); PV_D0(1); PV_D0(2); PV_D0(3);
;     ...
; }
.LBB0_1299:
	global_load_dwordx2 v[146:147], v179, s[68:69] offset:-8
	s_add_u32 s98, s16, 0x40000
	s_addc_u32 s99, s17, 0
	global_load_dwordx4 v[130:133], v188, s[98:99]
	s_add_u32 s98, s16, 0x50000
	s_addc_u32 s99, s17, 0
	global_load_dwordx4 v[134:137], v188, s[98:99]
	s_add_u32 s98, s100, 0x40000
	s_addc_u32 s99, s101, 0
	global_load_dwordx4 v[138:141], v188, s[98:99]
	s_add_u32 s98, s100, 0x50000
	s_addc_u32 s99, s101, 0
	global_load_dwordx4 v[142:145], v188, s[98:99]
	ds_read_b128 v[66:69], v199 offset:49152
	ds_read_b128 v[82:85], v199 offset:57344
	ds_read_b128 v[172:175], v200 offset:49152
	ds_read_b128 v[232:235], v200 offset:57344
	ds_read_b128 v[236:239], v201 offset:49152
	ds_read_b128 v[240:243], v201 offset:57344
	ds_read_b128 v[244:247], v202 offset:49152
	v_exp_f32_e32 v209, v150
	v_add_f32_e32 v150, v220, v219
	v_add_f32_e32 v150, v221, v150
	v_add_f32_e32 v150, v222, v150
	v_add_f32_e32 v150, v223, v150
	v_add_f32_e32 v150, v225, v150
	v_add_f32_e32 v150, v224, v150
	v_add_f32_e32 v150, v226, v150
	v_add_f32_e32 v150, v211, v150
	v_add_f32_e32 v150, v212, v150
	v_exp_f32_e32 v194, v194
	v_exp_f32_e32 v195, v195
	v_exp_f32_e32 v192, v192
	v_exp_f32_e32 v193, v193
	v_exp_f32_e32 v158, v158
	s_waitcnt lgkmcnt(6)
	v_mfma_f32_32x32x16_bf16 v[66:81], v[66:69], v[126:129], 0
	s_waitcnt lgkmcnt(5)
	v_mfma_f32_32x32x16_bf16 v[82:97], v[82:85], v[126:129], 0
	s_waitcnt lgkmcnt(4)
	v_mfma_f32_32x32x16_bf16 v[66:81], v[172:175], v[122:125], v[66:81]
	ds_read_b128 v[172:175], v202 offset:57344
	s_waitcnt lgkmcnt(4)
	v_mfma_f32_32x32x16_bf16 v[82:97], v[232:235], v[122:125], v[82:97]
	ds_read_b128 v[232:235], v199 offset:49280
	v_exp_f32_e32 v159, v159
	s_waitcnt lgkmcnt(4)
	v_mfma_f32_32x32x16_bf16 v[66:81], v[236:239], v[118:121], v[66:81]
	ds_read_b128 v[236:239], v199 offset:57472
	v_exp_f32_e32 v207, v154
	v_exp_f32_e32 v208, v155
	v_exp_f32_e32 v210, v151
	s_waitcnt lgkmcnt(4)
	v_mfma_f32_32x32x16_bf16 v[82:97], v[240:243], v[118:121], v[82:97]
	ds_read_b128 v[240:243], v200 offset:49280
	v_exp_f32_e32 v160, v160
	v_exp_f32_e32 v161, v161
	s_waitcnt lgkmcnt(4)
	v_mfma_f32_32x32x16_bf16 v[66:81], v[244:247], v[114:117], v[66:81]
	ds_read_b128 v[244:247], v200 offset:57472
	v_exp_f32_e32 v227, v156
	v_cvt_pk_bf16_f32 v151, v224, v226
	v_cvt_pk_bf16_f32 v154, v214, v216
	v_cvt_pk_bf16_f32 v155, v217, v218
	v_cvt_pk_bf16_f32 v156, v194, v195
	s_waitcnt lgkmcnt(4)
	v_mfma_f32_32x32x16_bf16 v[82:97], v[172:175], v[114:117], v[82:97]
	ds_read_b128 v[172:175], v201 offset:49280
	v_exp_f32_e32 v228, v157
	v_exp_f32_e32 v229, v152
	s_waitcnt lgkmcnt(4)
	v_mfma_f32_32x32x16_bf16 v[66:81], v[232:235], v[110:113], v[66:81]
	ds_read_b128 v[232:235], v201 offset:57472
	v_exp_f32_e32 v230, v153
	v_cvt_pk_bf16_f32 v152, v211, v212
	v_cvt_pk_bf16_f32 v153, v213, v215
	v_cvt_pk_bf16_f32 v157, v192, v193
	v_cvt_pk_bf16_f32 v211, v229, v230
	s_waitcnt lgkmcnt(4)
	v_mfma_f32_32x32x16_bf16 v[82:97], v[236:239], v[110:113], v[82:97]
	ds_read_b128 v[236:239], v202 offset:49280
	v_add_f32_e32 v249, v213, v150
	v_add_f32_e32 v249, v215, v249
	v_add_f32_e32 v249, v214, v249
	s_waitcnt lgkmcnt(4)
	v_mfma_f32_32x32x16_bf16 v[66:81], v[240:243], v[106:109], v[66:81]
	ds_read_b128 v[240:243], v202 offset:57472
	v_add_f32_e32 v249, v216, v249
	v_add_f32_e32 v249, v217, v249
	v_add_f32_e32 v249, v218, v249
	v_add_f32_e32 v249, v194, v249
	v_add_f32_e32 v248, v195, v249
	s_waitcnt lgkmcnt(4)
	v_mfma_f32_32x32x16_bf16 v[82:97], v[244:247], v[106:109], v[82:97]
	v_add_f32_e32 v248, v192, v248
	v_add_f32_e32 v248, v193, v248
	v_add_f32_e32 v248, v158, v248
	v_add_f32_e32 v248, v159, v248
	v_add_f32_e32 v248, v207, v248
	s_waitcnt lgkmcnt(3)
	v_mfma_f32_32x32x16_bf16 v[66:81], v[172:175], v[102:105], v[66:81]
	v_add_f32_e32 v248, v208, v248
	v_add_f32_e32 v248, v209, v248
	v_add_f32_e32 v248, v210, v248
	v_add_f32_e32 v248, v160, v248
	v_add_f32_e32 v248, v161, v248
	s_waitcnt lgkmcnt(2)
	v_mfma_f32_32x32x16_bf16 v[82:97], v[232:235], v[102:105], v[82:97]
	v_add_f32_e32 v248, v227, v248
	v_add_f32_e32 v248, v228, v248
	v_add_f32_e32 v248, v229, v248
	v_add_f32_e32 v181, v230, v248
	s_waitcnt lgkmcnt(1)
	v_mfma_f32_32x32x16_bf16 v[66:81], v[236:239], v[98:101], v[66:81]
	v_cvt_pk_bf16_f32 v148, v219, v220
	v_cvt_pk_bf16_f32 v149, v221, v222
	v_cvt_pk_bf16_f32 v150, v223, v225
	v_cvt_pk_bf16_f32 v158, v158, v159
	v_cvt_pk_bf16_f32 v159, v207, v208
	s_waitcnt lgkmcnt(0)
	v_mfma_f32_32x32x16_bf16 v[82:97], v[240:243], v[98:101], v[82:97]
	v_cvt_pk_bf16_f32 v208, v209, v210
	v_cvt_pk_bf16_f32 v210, v227, v228
	v_cvt_pk_bf16_f32 v209, v160, v161
	ds_read_b64_tr_b16 v[172:173], v1 offset:0x0
	ds_read_b64_tr_b16 v[174:175], v1 offset:0x800
	ds_read_b64_tr_b16 v[212:213], v1 offset:0x200
	ds_read_b64_tr_b16 v[214:215], v1 offset:0xa00
	ds_read_b64_tr_b16 v[216:217], v1 offset:0x400
	ds_read_b64_tr_b16 v[218:219], v1 offset:0xc00
	ds_read_b64_tr_b16 v[220:221], v1 offset:0x600
	ds_read_b64_tr_b16 v[222:223], v1 offset:0xe00
	ds_read_b64_tr_b16 v[224:225], v1 offset:0x1000
	ds_read_b64_tr_b16 v[226:227], v1 offset:0x1800
	ds_read_b64_tr_b16 v[232:233], v1 offset:0x1200
	ds_read_b64_tr_b16 v[234:235], v1 offset:0x1a00
	ds_read_b64_tr_b16 v[236:237], v1 offset:0x1400
	ds_read_b64_tr_b16 v[238:239], v1 offset:0x1c00
	s_nop 0
	s_waitcnt vmcnt(4)
; __device__ __forceinline__ void sel_mask_tile(f32x16& p0, f32x16& p1, unsigned wlo, unsigned whi, int hi) {
;     const unsigned NEGB = 0xff800000u;
;     const unsigned lo = wlo >> (4 * hi), h2 = whi >> (4 * hi);
; #pragma unroll
;     for (int r = 0; r < 16; ++r) {
;         const int c = (r & 3) + 8 * (r >> 2);
;         const unsigned m0 = (unsigned)__builtin_amdgcn_sbfe((int)lo, c, 1), m1 = (unsigned)__builtin_amdgcn_sbfe((int)h2, c, 1);
;         p0[r] = __uint_as_float((__float_as_uint(p0[r]) & m0) | (NEGB & ~m0));
;         p1[r] = __uint_as_float((__float_as_uint(p1[r]) & m1) | (NEGB & ~m1));
;     }
; }
; __device__ __forceinline__ void partialSM(f32x16& p0, f32x16& p1, float& m_reg, float& mn, float& alpha) {
;     float pmax = p0[0];
; #pragma unroll
;     for (int r = 1; r < 16; ++r) pmax = fmaxf(pmax, p0[r]);
; #pragma unroll
;     for (int r = 0; r < 16; ++r) pmax = fmaxf(pmax, p1[r]);
;     { auto rr = __builtin_amdgcn_permlane32_swap(__float_as_uint(pmax), __float_as_uint(pmax), false, false);
;       pmax = fmaxf(__uint_as_float(rr[0]), __uint_as_float(rr[1])); }
;     constexpr float C2 = 1.4426950408889634f * SCALE;
;     if (__builtin_expect(__all((pmax - m_reg) * SCALE <= THR), 1)) { mn = m_reg; alpha = 1.f; }
;     else { mn = fmaxf(m_reg, pmax); alpha = __builtin_amdgcn_exp2f((m_reg - mn) * C2); m_reg = mn; }
;     const float mnL = -mn * C2;
; #pragma unroll
;     for (int r = 0; r < 16; ++r) p0[r] = fmaf(p0[r], C2, mnL);
; #pragma unroll
;     for (int r = 0; r < 16; ++r) p1[r] = fmaf(p1[r], C2, mnL);
; #pragma unroll
;     for (int r = 0; r < 16; ++r) p0[r] = __builtin_amdgcn_exp2f(p0[r]);
; }
; template <int VB>
; __device__ __forceinline__ void pv_tile(f32x16* o, int vb0, bf16x8 pa0, bf16x8 pa1, bf16x8 pa2, bf16x8 pa3) {
;     ...
;     PV_D0(0); PV_D0(1); PV_D0(2); PV_D0(3);
;     ...
; }
	v_lshrrev_b32_e32 v160, v163, v146
	v_lshrrev_b32_e32 v161, v163, v147
	v_bfe_i32 v146, v160, 0, 1
	v_bfe_i32 v147, v161, 0, 1
	v_bitop3_b32 v146, v66, s74, v146 bitop3:0xe4
	v_bitop3_b32 v66, v82, s74, v147 bitop3:0xe4
	v_bfe_i32 v82, v160, 1, 1
	v_bfe_i32 v147, v161, 1, 1
	v_bitop3_b32 v82, v67, s74, v82 bitop3:0xe4
	v_bitop3_b32 v67, v83, s74, v147 bitop3:0xe4
	v_bfe_i32 v83, v160, 2, 1
	v_bfe_i32 v147, v161, 2, 1
	v_bitop3_b32 v83, v68, s74, v83 bitop3:0xe4
	v_bitop3_b32 v68, v84, s74, v147 bitop3:0xe4
	v_bfe_i32 v84, v160, 3, 1
	s_waitcnt lgkmcnt(12)
	v_mfma_f32_32x32x16_bf16 v[2:17], v[148:151], v[172:175], v[2:17]
	ds_read_b64_tr_b16 v[240:241], v1 offset:0x1600
	ds_read_b64_tr_b16 v[242:243], v1 offset:0x1e00
	s_waitcnt lgkmcnt(12)
	v_mfma_f32_32x32x16_bf16 v[50:65], v[148:151], v[212:215], v[50:65]
	ds_read_b64_tr_b16 v[244:245], v1 offset:0x2000
	ds_read_b64_tr_b16 v[246:247], v1 offset:0x2800
	s_waitcnt lgkmcnt(12)
	v_mfma_f32_32x32x16_bf16 v[34:49], v[148:151], v[216:219], v[34:49]
	ds_read_b64_tr_b16 v[248:249], v1 offset:0x2200
	ds_read_b64_tr_b16 v[250:251], v1 offset:0x2a00
	s_waitcnt lgkmcnt(12)
	v_mfma_f32_32x32x16_bf16 v[18:33], v[148:151], v[220:223], v[18:33]
	ds_read_b64_tr_b16 v[220:221], v1 offset:0x2400
	ds_read_b64_tr_b16 v[222:223], v1 offset:0x2c00
	v_bfe_i32 v148, v161, 3, 1
	v_bitop3_b32 v147, v69, s74, v84 bitop3:0xe4
	v_bfe_i32 v84, v160, 8, 1
	v_bitop3_b32 v69, v85, s74, v148 bitop3:0xe4
	v_bfe_i32 v85, v161, 8, 1
	v_bitop3_b32 v148, v70, s74, v84 bitop3:0xe4
	s_waitcnt lgkmcnt(12)
	v_mfma_f32_32x32x16_bf16 v[2:17], v[152:155], v[224:227], v[2:17]
	ds_read_b64_tr_b16 v[224:225], v1 offset:0x2600
	ds_read_b64_tr_b16 v[226:227], v1 offset:0x2e00
	v_bfe_i32 v84, v160, 9, 1
	v_bitop3_b32 v70, v86, s74, v85 bitop3:0xe4
	v_bfe_i32 v85, v161, 9, 1
	v_bitop3_b32 v149, v71, s74, v84 bitop3:0xe4
	v_bfe_i32 v84, v160, 10, 1
	v_bitop3_b32 v71, v87, s74, v85 bitop3:0xe4
	s_waitcnt lgkmcnt(12)
	v_mfma_f32_32x32x16_bf16 v[50:65], v[152:155], v[232:235], v[50:65]
	ds_read_b64_tr_b16 v[232:233], v1 offset:0x3000
	ds_read_b64_tr_b16 v[234:235], v1 offset:0x3800
	v_bfe_i32 v85, v161, 10, 1
	v_bitop3_b32 v87, v72, s74, v84 bitop3:0xe4
	v_bfe_i32 v84, v160, 11, 1
	v_bitop3_b32 v72, v88, s74, v85 bitop3:0xe4
	v_bfe_i32 v85, v161, 11, 1
	v_bitop3_b32 v88, v73, s74, v84 bitop3:0xe4
	s_waitcnt lgkmcnt(12)
	v_mfma_f32_32x32x16_bf16 v[34:49], v[152:155], v[236:239], v[34:49]
	ds_read_b64_tr_b16 v[236:237], v1 offset:0x3200
	ds_read_b64_tr_b16 v[238:239], v1 offset:0x3a00
	v_bfe_i32 v73, v160, 16, 1
	v_bitop3_b32 v84, v89, s74, v85 bitop3:0xe4
	v_bfe_i32 v85, v161, 16, 1
	v_bitop3_b32 v89, v74, s74, v73 bitop3:0xe4
	v_bfe_i32 v73, v160, 17, 1
	v_bfe_i32 v74, v161, 17, 1
	s_waitcnt lgkmcnt(12)
	v_mfma_f32_32x32x16_bf16 v[18:33], v[152:155], v[240:243], v[18:33]
	ds_read_b64_tr_b16 v[240:241], v1 offset:0x3400
	ds_read_b64_tr_b16 v[242:243], v1 offset:0x3c00
	v_bitop3_b32 v85, v90, s74, v85 bitop3:0xe4
	v_bitop3_b32 v90, v75, s74, v73 bitop3:0xe4
	v_bitop3_b32 v86, v91, s74, v74 bitop3:0xe4
	v_bfe_i32 v73, v160, 18, 1
	v_bfe_i32 v74, v161, 18, 1
	v_bitop3_b32 v91, v76, s74, v73 bitop3:0xe4
	s_waitcnt lgkmcnt(12)
	v_mfma_f32_32x32x16_bf16 v[2:17], v[156:159], v[244:247], v[2:17]
	ds_read_b64_tr_b16 v[244:245], v1 offset:0x3600
	ds_read_b64_tr_b16 v[246:247], v1 offset:0x3e00
	v_bitop3_b32 v76, v92, s74, v74 bitop3:0xe4
	v_bfe_i32 v73, v160, 19, 1
	v_bfe_i32 v74, v161, 19, 1
	v_bitop3_b32 v92, v77, s74, v73 bitop3:0xe4
	v_bitop3_b32 v77, v93, s74, v74 bitop3:0xe4
	s_waitcnt lgkmcnt(12)
	v_mfma_f32_32x32x16_bf16 v[50:65], v[156:159], v[248:251], v[50:65]
	v_bfe_i32 v73, v160, 24, 1
	v_bfe_i32 v74, v161, 24, 1
	v_bitop3_b32 v93, v78, s74, v73 bitop3:0xe4
	v_bitop3_b32 v78, v94, s74, v74 bitop3:0xe4
	v_bfe_i32 v73, v160, 25, 1
	v_bfe_i32 v74, v161, 25, 1
	s_waitcnt lgkmcnt(10)
	v_mfma_f32_32x32x16_bf16 v[34:49], v[156:159], v[220:223], v[34:49]
	v_bitop3_b32 v79, v79, s74, v73 bitop3:0xe4
	v_bitop3_b32 v73, v95, s74, v74 bitop3:0xe4
	v_bfe_i32 v74, v160, 26, 1
	v_bfe_i32 v75, v161, 26, 1
	v_bitop3_b32 v80, v80, s74, v74 bitop3:0xe4
	s_waitcnt lgkmcnt(8)
	v_mfma_f32_32x32x16_bf16 v[18:33], v[156:159], v[224:227], v[18:33]
	v_bitop3_b32 v74, v96, s74, v75 bitop3:0xe4
	v_bfe_i32 v75, v160, 27, 1
	v_bfe_i32 v94, v161, 27, 1
	v_bitop3_b32 v81, v81, s74, v75 bitop3:0xe4
	v_bitop3_b32 v75, v97, s74, v94 bitop3:0xe4
	v_max_f32_e32 v94, v146, v82
	s_waitcnt lgkmcnt(6)
	v_mfma_f32_32x32x16_bf16 v[2:17], v[208:211], v[232:235], v[2:17]
	v_max3_f32 v94, v94, v83, v147
	v_max3_f32 v94, v94, v148, v149
	v_max3_f32 v94, v94, v87, v88
	v_max3_f32 v94, v94, v89, v90
	v_max3_f32 v94, v94, v91, v92
	s_waitcnt lgkmcnt(4)
	v_mfma_f32_32x32x16_bf16 v[50:65], v[208:211], v[236:239], v[50:65]
	v_max3_f32 v94, v94, v93, v79
	v_max3_f32 v94, v94, v80, v81
	v_max3_f32 v94, v94, v66, v67
	v_max3_f32 v94, v94, v68, v69
	v_max3_f32 v94, v94, v70, v71
	v_max3_f32 v94, v94, v72, v84
	s_waitcnt lgkmcnt(2)
	v_mfma_f32_32x32x16_bf16 v[34:49], v[208:211], v[240:243], v[34:49]
	v_max3_f32 v94, v94, v85, v86
	v_max3_f32 v94, v94, v76, v77
	v_max3_f32 v94, v94, v78, v73
	v_max3_f32 v94, v94, v74, v75
	v_mov_b32_e32 v95, v94
	s_nop 1
	s_waitcnt lgkmcnt(0)
	v_mfma_f32_32x32x16_bf16 v[18:33], v[208:211], v[244:247], v[18:33]
	s_waitcnt vmcnt(0)
	ds_write_b128 v204, v[138:141] offset:32768
	ds_write_b128 v204, v[142:145] offset:40960
	v_permlane32_swap_b32_e32 v94, v95
	v_max_f32_e32 v94, v94, v95
	v_sub_f32_e32 v95, v94, v206
	v_mul_f32_e32 v95, 0x3db504f3, v95
	v_cmp_ge_f32_e32 vcc, s75, v95
	s_cmp_eq_u64 vcc, exec
	s_cselect_b64 s[6:7], -1, 0
	s_cbranch_scc1 .Lp5_b1fast
	v_max_f32_e32 v94, v206, v94
	v_sub_f32_e32 v96, v206, v94
	v_mul_f32_e32 v96, 0x3e0293ee, v96
	v_exp_f32_e32 v96, v96

; __device__ __forceinline__ void finishSM(f32x16& p0, f32x16& p1, float alpha, float& l_reg, bf16x8& pa0, bf16x8& pa1, bf16x8& pa2, bf16x8& pa3) {
; #pragma unroll
;     for (int r = 0; r < 16; ++r) p1[r] = __builtin_amdgcn_exp2f(p1[r]);
;     float ps = 0;
; #pragma unroll
;     for (int r = 0; r < 16; ++r) ps += p0[r];
; #pragma unroll
;     for (int r = 0; r < 16; ++r) ps += p1[r];
;     { auto rr = __builtin_amdgcn_permlane32_swap(__float_as_uint(ps), __float_as_uint(ps), false, false);
;       ps = __uint_as_float(rr[0]) + __uint_as_float(rr[1]); }
;     l_reg = l_reg * alpha + ps;
;     ...
;     PK4(p0, 0, pa0); PK4(p0, 8, pa1); PK4(p1, 0, pa2); PK4(p1, 8, pa3);
;     ...
; }
; template <int KB>
; __device__ __forceinline__ void qkt(f32x16& p0, f32x16& p1, const char* K_lds, int r32, int hi, const bf16x8* qr) {
;     p0 = f32x16{}; p1 = f32x16{};
;     const char* kb[4];
; #pragma unroll
;     for (int dd = 0; dd < 4; ++dd) kb[dd] = K_lds + KB * SHM_K + KSWZ(r32, (dd * 16 + hi * 8) * 2);
; #pragma unroll
;     for (int d0 = 0; d0 < 8; ++d0) { const char* a = kb[d0 & 3] + (d0 >> 2) * 128;
;         bf16x8 b0 = *reinterpret_cast<const bf16x8*>(a);
;         bf16x8 b1 = *reinterpret_cast<const bf16x8*>(a + 32 * 256);
;         p0 = __builtin_amdgcn_mfma_f32_32x32x16_bf16(b0, qr[d0], p0, 0, 0, 0);
;         p1 = __builtin_amdgcn_mfma_f32_32x32x16_bf16(b1, qr[d0], p1, 0, 0, 0); }
; }
.Lp5_a2:
	ds_read_b128 v[66:69], v199 offset:32768
	ds_read_b128 v[70:73], v199 offset:40960
	ds_read_b128 v[172:175], v200 offset:32768
	ds_read_b128 v[224:227], v200 offset:40960
	ds_read_b128 v[232:235], v201 offset:32768
	ds_read_b128 v[236:239], v201 offset:40960
	ds_read_b128 v[240:243], v202 offset:32768
	ds_read_b128 v[244:247], v202 offset:40960
	v_exp_f32_e32 v211, v211
	v_exp_f32_e32 v212, v212
	v_exp_f32_e32 v213, v213
	v_exp_f32_e32 v214, v214
	v_exp_f32_e32 v215, v215
	v_exp_f32_e32 v216, v216
	v_exp_f32_e32 v207, v207
	v_exp_f32_e32 v250, v219
	v_exp_f32_e32 v219, v209
	v_add_f32_e32 v209, v147, v146
	v_add_f32_e32 v209, v148, v209
	v_add_f32_e32 v209, v159, v209
	v_add_f32_e32 v209, v160, v209
	v_add_f32_e32 v209, v161, v209
	s_waitcnt lgkmcnt(7)
	v_mfma_f32_32x32x16_bf16 v[82:97], v[66:69], v[126:129], 0
	s_waitcnt lgkmcnt(6)
	v_mfma_f32_32x32x16_bf16 v[66:81], v[70:73], v[126:129], 0
	s_waitcnt lgkmcnt(5)
	v_mfma_f32_32x32x16_bf16 v[82:97], v[172:175], v[122:125], v[82:97]
	ds_read_b128 v[172:175], v199 offset:32896
	s_waitcnt lgkmcnt(5)
	v_mfma_f32_32x32x16_bf16 v[66:81], v[224:227], v[122:125], v[66:81]
	ds_read_b128 v[224:227], v199 offset:41088
	v_add_f32_e32 v209, v149, v209
	s_waitcnt lgkmcnt(5)
	v_mfma_f32_32x32x16_bf16 v[82:97], v[232:235], v[118:121], v[82:97]
	ds_read_b128 v[232:235], v200 offset:32896
	v_add_f32_e32 v209, v158, v209
	v_add_f32_e32 v209, v150, v209
	v_add_f32_e32 v209, v151, v209
	v_add_f32_e32 v209, v155, v209
	v_add_f32_e32 v209, v157, v209
	s_waitcnt lgkmcnt(5)
	v_mfma_f32_32x32x16_bf16 v[66:81], v[236:239], v[118:121], v[66:81]
	ds_read_b128 v[236:239], v200 offset:41088
	v_exp_f32_e32 v248, v217
	v_add_f32_e32 v209, v152, v209
	v_exp_f32_e32 v249, v218
	s_waitcnt lgkmcnt(5)
	v_mfma_f32_32x32x16_bf16 v[82:97], v[240:243], v[114:117], v[82:97]
	ds_read_b128 v[240:243], v201 offset:32896
	v_add_f32_e32 v209, v153, v209
	v_add_f32_e32 v209, v154, v209
	v_exp_f32_e32 v251, v220
	v_add_f32_e32 v209, v156, v209
	s_waitcnt lgkmcnt(5)
	v_mfma_f32_32x32x16_bf16 v[66:81], v[244:247], v[114:117], v[66:81]
	ds_read_b128 v[244:247], v201 offset:41088
	v_exp_f32_e32 v217, v221
	v_add_f32_e32 v209, v248, v209
	v_exp_f32_e32 v218, v210
	s_waitcnt lgkmcnt(5)
	v_mfma_f32_32x32x16_bf16 v[82:97], v[172:175], v[110:113], v[82:97]
	ds_read_b128 v[172:175], v202 offset:32896
	v_add_f32_e32 v209, v249, v209
	v_add_f32_e32 v209, v250, v209
	v_add_f32_e32 v209, v251, v209
	v_add_f32_e32 v209, v217, v209
	v_add_f32_e32 v209, v218, v209
	s_waitcnt lgkmcnt(5)
	v_mfma_f32_32x32x16_bf16 v[66:81], v[224:227], v[110:113], v[66:81]
	ds_read_b128 v[224:227], v202 offset:41088
	v_add_f32_e32 v209, v211, v209
	v_add_f32_e32 v209, v212, v209
	v_add_f32_e32 v209, v213, v209
	v_exp_f32_e32 v220, v222
	s_waitcnt lgkmcnt(5)
	v_mfma_f32_32x32x16_bf16 v[82:97], v[232:235], v[106:109], v[82:97]
	v_add_f32_e32 v209, v214, v209
	v_exp_f32_e32 v221, v223
	v_add_f32_e32 v209, v215, v209
	v_add_f32_e32 v209, v216, v209
	s_waitcnt lgkmcnt(4)
	v_mfma_f32_32x32x16_bf16 v[66:81], v[236:239], v[106:109], v[66:81]
	v_add_f32_e32 v209, v219, v209
	v_add_f32_e32 v209, v220, v209
	v_add_f32_e32 v209, v221, v209
	v_add_f32_e32 v209, v207, v209
	s_waitcnt lgkmcnt(3)
	v_mfma_f32_32x32x16_bf16 v[82:97], v[240:243], v[102:105], v[82:97]
	v_cvt_pk_bf16_f32 v146, v146, v147
	v_cvt_pk_bf16_f32 v147, v148, v159
	v_cvt_pk_bf16_f32 v148, v160, v161
	v_cvt_pk_bf16_f32 v149, v149, v158
	v_cvt_pk_bf16_f32 v150, v150, v151
	s_waitcnt lgkmcnt(2)
	v_mfma_f32_32x32x16_bf16 v[66:81], v[244:247], v[102:105], v[66:81]
	v_cvt_pk_bf16_f32 v151, v155, v157
	v_cvt_pk_bf16_f32 v152, v152, v153
	v_cvt_pk_bf16_f32 v153, v154, v156
	v_cvt_pk_bf16_f32 v154, v248, v249
	v_cvt_pk_bf16_f32 v155, v250, v251
	s_waitcnt lgkmcnt(1)
	v_mfma_f32_32x32x16_bf16 v[82:97], v[172:175], v[98:101], v[82:97]
	v_cvt_pk_bf16_f32 v156, v217, v218
	v_cvt_pk_bf16_f32 v157, v211, v212
	v_cvt_pk_bf16_f32 v158, v213, v214
	v_cvt_pk_bf16_f32 v159, v215, v216
	v_cvt_pk_bf16_f32 v160, v219, v220
	s_waitcnt lgkmcnt(0)
	v_mfma_f32_32x32x16_bf16 v[66:81], v[224:227], v[98:101], v[66:81]
	v_cvt_pk_bf16_f32 v161, v221, v207
	s_add_i32 s82, s82, 2
	s_cmp_le_u32 s82, s81
	s_cselect_b64 s[36:37], -1, 0
	s_cmp_gt_u32 s82, s81
	s_cbranch_scc1 .Lp5_skip_ld
; __device__ __forceinline__ void sel_mask_tile(f32x16& p0, f32x16& p1, unsigned wlo, unsigned whi, int hi) {
;     const unsigned NEGB = 0xff800000u;
;     const unsigned lo = wlo >> (4 * hi), h2 = whi >> (4 * hi);
; #pragma unroll
;     for (int r = 0; r < 16; ++r) {
;         const int c = (r & 3) + 8 * (r >> 2);
;         const unsigned m0 = (unsigned)__builtin_amdgcn_sbfe((int)lo, c, 1), m1 = (unsigned)__builtin_amdgcn_sbfe((int)h2, c, 1);
;         p0[r] = __uint_as_float((__float_as_uint(p0[r]) & m0) | (NEGB & ~m0));
;         p1[r] = __uint_as_float((__float_as_uint(p1[r]) & m1) | (NEGB & ~m1));
;     }
; }
; __device__ __forceinline__ void partialSM(f32x16& p0, f32x16& p1, float& m_reg, float& mn, float& alpha) {
;     float pmax = p0[0];
; #pragma unroll
;     for (int r = 1; r < 16; ++r) pmax = fmaxf(pmax, p0[r]);
; #pragma unroll
;     for (int r = 0; r < 16; ++r) pmax = fmaxf(pmax, p1[r]);
;     { auto rr = __builtin_amdgcn_permlane32_swap(__float_as_uint(pmax), __float_as_uint(pmax), false, false);
;       pmax = fmaxf(__uint_as_float(rr[0]), __uint_as_float(rr[1])); }
;     constexpr float C2 = 1.4426950408889634f * SCALE;
;     if (__builtin_expect(__all((pmax - m_reg) * SCALE <= THR), 1)) { mn = m_reg; alpha = 1.f; }
; template <int VB>
; __device__ __forceinline__ void pv_tile(f32x16* o, int vb0, bf16x8 pa0, bf16x8 pa1, bf16x8 pa2, bf16x8 pa3) {
;     ...
;     PV_D0(0); PV_D0(1); PV_D0(2); PV_D0(3);
.LBB0_1305:
	ds_read_b64_tr_b16 v[212:213], v1 offset:0x4000
	ds_read_b64_tr_b16 v[214:215], v1 offset:0x4800
	ds_read_b64_tr_b16 v[216:217], v1 offset:0x4200
	ds_read_b64_tr_b16 v[218:219], v1 offset:0x4a00
	ds_read_b64_tr_b16 v[220:221], v1 offset:0x4400
	ds_read_b64_tr_b16 v[222:223], v1 offset:0x4c00
	ds_read_b64_tr_b16 v[224:225], v1 offset:0x4600
	ds_read_b64_tr_b16 v[226:227], v1 offset:0x4e00
	ds_read_b64_tr_b16 v[232:233], v1 offset:0x5000
	ds_read_b64_tr_b16 v[234:235], v1 offset:0x5800
	ds_read_b64_tr_b16 v[236:237], v1 offset:0x5200
	ds_read_b64_tr_b16 v[238:239], v1 offset:0x5a00
	ds_read_b64_tr_b16 v[240:241], v1 offset:0x5400
	ds_read_b64_tr_b16 v[242:243], v1 offset:0x5c00
	s_nop 0
	s_waitcnt vmcnt(4)
	v_lshrrev_b32_e32 v193, v163, v228
	v_bfe_i32 v192, v193, 0, 1
	v_bitop3_b32 v192, v82, s74, v192 bitop3:0xe4
	v_bfe_i32 v82, v193, 1, 1
	s_waitcnt lgkmcnt(12)
	v_mfma_f32_32x32x16_bf16 v[2:17], v[146:149], v[212:215], v[2:17]
	ds_read_b64_tr_b16 v[244:245], v1 offset:0x5600
	ds_read_b64_tr_b16 v[246:247], v1 offset:0x5e00
	s_waitcnt lgkmcnt(12)
	v_mfma_f32_32x32x16_bf16 v[50:65], v[146:149], v[216:219], v[50:65]
	ds_read_b64_tr_b16 v[248:249], v1 offset:0x6000
	ds_read_b64_tr_b16 v[250:251], v1 offset:0x6800
	s_waitcnt lgkmcnt(12)
	v_mfma_f32_32x32x16_bf16 v[34:49], v[146:149], v[220:223], v[34:49]
	ds_read_b64_tr_b16 v[220:221], v1 offset:0x6200
	ds_read_b64_tr_b16 v[222:223], v1 offset:0x6a00
	s_waitcnt lgkmcnt(12)
	v_mfma_f32_32x32x16_bf16 v[18:33], v[146:149], v[224:227], v[18:33]
	ds_read_b64_tr_b16 v[224:225], v1 offset:0x6400
	ds_read_b64_tr_b16 v[226:227], v1 offset:0x6c00
	v_bitop3_b32 v146, v83, s74, v82 bitop3:0xe4
	v_bfe_i32 v82, v193, 2, 1
	v_bitop3_b32 v147, v84, s74, v82 bitop3:0xe4
	v_bfe_i32 v82, v193, 3, 1
	v_bitop3_b32 v148, v85, s74, v82 bitop3:0xe4
	v_bfe_i32 v82, v193, 8, 1
	v_bitop3_b32 v149, v86, s74, v82 bitop3:0xe4
	s_waitcnt lgkmcnt(12)
	v_mfma_f32_32x32x16_bf16 v[2:17], v[150:153], v[232:235], v[2:17]
	ds_read_b64_tr_b16 v[232:233], v1 offset:0x6600
	ds_read_b64_tr_b16 v[234:235], v1 offset:0x6e00
	v_bfe_i32 v82, v193, 9, 1
	s_waitcnt lgkmcnt(12)
	v_mfma_f32_32x32x16_bf16 v[50:65], v[150:153], v[236:239], v[50:65]
	ds_read_b64_tr_b16 v[236:237], v1 offset:0x7000
	ds_read_b64_tr_b16 v[238:239], v1 offset:0x7800
	s_waitcnt lgkmcnt(12)
	v_mfma_f32_32x32x16_bf16 v[34:49], v[150:153], v[240:243], v[34:49]
	ds_read_b64_tr_b16 v[240:241], v1 offset:0x7200
	ds_read_b64_tr_b16 v[242:243], v1 offset:0x7a00
	s_waitcnt lgkmcnt(12)
	v_mfma_f32_32x32x16_bf16 v[18:33], v[150:153], v[244:247], v[18:33]
	ds_read_b64_tr_b16 v[244:245], v1 offset:0x7400
	ds_read_b64_tr_b16 v[246:247], v1 offset:0x7c00
	v_bitop3_b32 v150, v87, s74, v82 bitop3:0xe4
	v_bfe_i32 v82, v193, 10, 1
	v_bitop3_b32 v88, v88, s74, v82 bitop3:0xe4
	v_bfe_i32 v82, v193, 11, 1
	v_bitop3_b32 v89, v89, s74, v82 bitop3:0xe4
	v_bfe_i32 v82, v193, 16, 1
	v_bitop3_b32 v90, v90, s74, v82 bitop3:0xe4
	v_bfe_i32 v82, v193, 17, 1
	v_bitop3_b32 v91, v91, s74, v82 bitop3:0xe4
	s_waitcnt lgkmcnt(12)
	v_mfma_f32_32x32x16_bf16 v[2:17], v[154:157], v[248:251], v[2:17]
	ds_read_b64_tr_b16 v[248:249], v1 offset:0x7600
	ds_read_b64_tr_b16 v[250:251], v1 offset:0x7e00
	v_bfe_i32 v82, v193, 18, 1
	v_bitop3_b32 v92, v92, s74, v82 bitop3:0xe4
	v_bfe_i32 v82, v193, 19, 1
	v_bitop3_b32 v93, v93, s74, v82 bitop3:0xe4
	v_bfe_i32 v82, v193, 24, 1
	v_bitop3_b32 v94, v94, s74, v82 bitop3:0xe4
	v_bfe_i32 v82, v193, 25, 1
	v_bitop3_b32 v95, v95, s74, v82 bitop3:0xe4
	s_waitcnt lgkmcnt(12)
	v_mfma_f32_32x32x16_bf16 v[50:65], v[154:157], v[220:223], v[50:65]
	v_bfe_i32 v82, v193, 26, 1
	v_bitop3_b32 v96, v96, s74, v82 bitop3:0xe4
	v_bfe_i32 v82, v193, 27, 1
	v_bitop3_b32 v97, v97, s74, v82 bitop3:0xe4
	v_max_f32_e32 v82, v192, v146
	v_max3_f32 v82, v82, v147, v148
	v_max3_f32 v82, v82, v149, v150
	v_max3_f32 v82, v82, v88, v89
	v_max3_f32 v82, v82, v90, v91
	s_waitcnt lgkmcnt(10)
	v_mfma_f32_32x32x16_bf16 v[34:49], v[154:157], v[224:227], v[34:49]
	v_lshrrev_b32_e32 v194, v163, v229
	v_max3_f32 v82, v82, v92, v93
	v_bfe_i32 v195, v194, 0, 1
	v_bfe_i32 v172, v194, 1, 1
	v_max3_f32 v82, v82, v94, v95
	v_bitop3_b32 v66, v66, s74, v195 bitop3:0xe4
	v_bfe_i32 v83, v194, 2, 1
	v_bfe_i32 v84, v194, 3, 1
	s_waitcnt lgkmcnt(8)
	v_mfma_f32_32x32x16_bf16 v[18:33], v[154:157], v[232:235], v[18:33]
	v_max3_f32 v230, v82, v96, v97
	v_bitop3_b32 v67, v67, s74, v172 bitop3:0xe4
	v_bfe_i32 v85, v194, 8, 1
	v_bfe_i32 v86, v194, 9, 1
	v_bitop3_b32 v82, v68, s74, v83 bitop3:0xe4
	v_max3_f32 v68, v230, v66, v67
	v_bitop3_b32 v83, v69, s74, v84 bitop3:0xe4
	v_bfe_i32 v87, v194, 10, 1
	v_bfe_i32 v151, v194, 11, 1
	s_waitcnt lgkmcnt(6)
	v_mfma_f32_32x32x16_bf16 v[2:17], v[158:161], v[236:239], v[2:17]
	v_bitop3_b32 v84, v70, s74, v85 bitop3:0xe4
	v_max3_f32 v68, v68, v82, v83
	v_bitop3_b32 v85, v71, s74, v86 bitop3:0xe4
	v_bfe_i32 v152, v194, 16, 1
	v_bfe_i32 v153, v194, 17, 1
	v_bitop3_b32 v86, v72, s74, v87 bitop3:0xe4
	v_max3_f32 v68, v68, v84, v85
	v_bitop3_b32 v87, v73, s74, v151 bitop3:0xe4
	s_waitcnt lgkmcnt(4)
	v_mfma_f32_32x32x16_bf16 v[50:65], v[158:161], v[240:243], v[50:65]
	v_bfe_i32 v154, v194, 18, 1
	v_bfe_i32 v155, v194, 19, 1
	v_bitop3_b32 v74, v74, s74, v152 bitop3:0xe4
	v_max3_f32 v69, v68, v86, v87
	v_bitop3_b32 v75, v75, s74, v153 bitop3:0xe4
	v_bfe_i32 v156, v194, 24, 1
	v_bfe_i32 v157, v194, 25, 1
	v_bitop3_b32 v68, v76, s74, v154 bitop3:0xe4
	v_max3_f32 v71, v69, v74, v75
	s_waitcnt lgkmcnt(2)
	v_mfma_f32_32x32x16_bf16 v[34:49], v[158:161], v[244:247], v[34:49]
	v_bitop3_b32 v69, v77, s74, v155 bitop3:0xe4
	v_bfe_i32 v230, v194, 26, 1
	v_bfe_i32 v231, v194, 27, 1
	v_bitop3_b32 v70, v78, s74, v156 bitop3:0xe4
	v_max3_f32 v73, v71, v68, v69
	v_bitop3_b32 v71, v79, s74, v157 bitop3:0xe4
	v_bitop3_b32 v72, v80, s74, v230 bitop3:0xe4
	v_max3_f32 v76, v73, v70, v71
	s_waitcnt lgkmcnt(0)
	v_mfma_f32_32x32x16_bf16 v[18:33], v[158:161], v[248:251], v[18:33]
	s_cmp_eq_u64 s[36:37], 0
	s_cbranch_scc1 .Lp5_kw2_skip
	s_waitcnt vmcnt(0)
	ds_write_b128 v204, v[138:141] offset:49152
	ds_write_b128 v204, v[142:145] offset:57344
.Lp5_kw2_skip:
	v_bitop3_b32 v73, v81, s74, v231 bitop3:0xe4
	v_max3_f32 v76, v76, v72, v73
	v_mov_b32_e32 v77, v76
	s_nop 1
	v_permlane32_swap_b32_e32 v76, v77
	v_max_f32_e32 v76, v76, v77
	v_sub_f32_e32 v77, v76, v206
	v_mul_f32_e32 v77, 0x3db504f3, v77
	v_cmp_ge_f32_e32 vcc, s75, v77
	s_cmp_eq_u64 vcc, exec
	s_cselect_b64 s[6:7], -1, 0
	s_andn2_b64 vcc, exec, s[36:37]
	s_barrier
	s_cbranch_vccnz .LBB0_1307
	s_waitcnt vmcnt(0)
	ds_write_b128 v197, v[130:133] offset:16384
	ds_write_b128 v198, v[134:137] offset:16384
